# c11 plus row-sum add tree in the P2 statistics passes
# speedup vs baseline: 1.0063x; 1.0001x over previous
.LBB0_660:
	v_bfe_u32 v169, v32, 5, 1
	s_ashr_i32 s76, s77, 6
	v_and_b32_e32 v168, 31, v32
	v_bitop3_b32 v0, v169, v32, 15 bitop3:0x78
	s_lshl_b32 s73, s76, 5
	v_lshlrev_b32_e32 v33, 8, v168
	v_lshlrev_b32_e32 v66, 4, v0
	s_add_i32 s1, s73, s78
	v_or_b32_e32 v8, v66, v33
	s_setprio 1
	s_cmp_lg_u32 0, -1
	s_cselect_b32 s2, 0, 0
	v_add_u32_e32 v182, s2, v8
	ds_read_b128 v[0:3], v182 offset:0x8000
	ds_read_b128 v[4:7], v182 offset:0xa000
	v_xad_u32 v181, v8, 32, s2
	ds_read_b128 v[34:37], v181 offset:0x8000
	ds_read_b128 v[38:41], v181 offset:0xa000
	v_xad_u32 v180, v8, 64, s2
	ds_read_b128 v[42:45], v180 offset:0x8000
	s_movk_i32 s3, 0x60
	ds_read_b128 v[46:49], v180 offset:0xa000
	v_bitop3_b32 v8, v66, s3, v33 bitop3:0x36
	v_add_u32_e32 v177, s2, v8
	ds_read_b128 v[50:53], v177 offset:0x8000
	ds_read_b128 v[54:57], v177 offset:0xa000
	s_waitcnt lgkmcnt(7)
	s_waitcnt vmcnt(7)
	v_mfma_f32_32x32x16_bf16 v[16:31], v[0:3], v[140:143], 0
	s_movk_i32 s3, 0x80
	v_bitop3_b32 v0, v66, s3, v33 bitop3:0x36
	v_add_u32_e32 v165, s2, v0
	ds_read_b128 v[58:61], v165 offset:0x8000
	s_waitcnt lgkmcnt(7)
	v_mfma_f32_32x32x16_bf16 v[0:15], v[4:7], v[140:143], 0
	ds_read_b128 v[62:65], v165 offset:0xa000
	s_waitcnt lgkmcnt(7)
	s_waitcnt vmcnt(6)
	v_mfma_f32_32x32x16_bf16 v[16:31], v[34:37], v[136:139], v[16:31]
	s_movk_i32 s3, 0xa0
	v_bitop3_b32 v34, v66, s3, v33 bitop3:0x36
	v_add_u32_e32 v176, s2, v34
	ds_read_b128 v[34:37], v176 offset:0x8000
	s_waitcnt lgkmcnt(7)
	v_mfma_f32_32x32x16_bf16 v[0:15], v[38:41], v[136:139], v[0:15]
	ds_read_b128 v[38:41], v176 offset:0xa000
	s_waitcnt lgkmcnt(7)
	s_waitcnt vmcnt(5)
	v_mfma_f32_32x32x16_bf16 v[16:31], v[42:45], v[132:135], v[16:31]
	s_movk_i32 s3, 0xc0
	v_bitop3_b32 v42, v66, s3, v33 bitop3:0x36
	v_add_u32_e32 v178, s2, v42
	ds_read_b128 v[42:45], v178 offset:0x8000
	s_waitcnt lgkmcnt(7)
	v_mfma_f32_32x32x16_bf16 v[0:15], v[46:49], v[132:135], v[0:15]
	ds_read_b128 v[46:49], v178 offset:0xa000
	s_waitcnt lgkmcnt(7)
	s_waitcnt vmcnt(4)
	v_mfma_f32_32x32x16_bf16 v[16:31], v[50:53], v[128:131], v[16:31]
	v_bitop3_b32 v33, v66, s20, v33 bitop3:0x36
	v_add_u32_e32 v179, s2, v33
	ds_read_b128 v[50:53], v179 offset:0x8000
	s_waitcnt lgkmcnt(7)
	v_mfma_f32_32x32x16_bf16 v[0:15], v[54:57], v[128:131], v[0:15]
	ds_read_b128 v[54:57], v179 offset:0xa000
	s_waitcnt lgkmcnt(7)
	s_waitcnt vmcnt(3)
	v_mfma_f32_32x32x16_bf16 v[16:31], v[58:61], v[124:127], v[16:31]
	s_waitcnt lgkmcnt(6)
	v_mfma_f32_32x32x16_bf16 v[0:15], v[62:65], v[124:127], v[0:15]
	s_waitcnt lgkmcnt(5)
	s_waitcnt vmcnt(2)
	v_mfma_f32_32x32x16_bf16 v[16:31], v[34:37], v[120:123], v[16:31]
	s_waitcnt lgkmcnt(4)
	v_mfma_f32_32x32x16_bf16 v[0:15], v[38:41], v[120:123], v[0:15]
	s_waitcnt lgkmcnt(3)
	s_waitcnt vmcnt(1)
	v_mfma_f32_32x32x16_bf16 v[16:31], v[42:45], v[116:119], v[16:31]
	s_waitcnt lgkmcnt(2)
	v_mfma_f32_32x32x16_bf16 v[0:15], v[46:49], v[116:119], v[0:15]
	s_waitcnt lgkmcnt(1)
	s_waitcnt vmcnt(0)
	v_mfma_f32_32x32x16_bf16 v[16:31], v[50:53], v[112:115], v[16:31]
	s_waitcnt lgkmcnt(0)
	v_mfma_f32_32x32x16_bf16 v[0:15], v[54:57], v[112:115], v[0:15]
	s_setprio 0
	s_waitcnt lgkmcnt(0)
	s_barrier
	s_cmp_gt_i32 s1, -1
	s_mov_b64 s[2:3], -1
	s_cbranch_scc0 .LBB0_662
	s_nop 5
	v_exp_f32_e32 v16, v16
	v_exp_f32_e32 v17, v17
	v_exp_f32_e32 v18, v18
	v_exp_f32_e32 v19, v19
	v_exp_f32_e32 v20, v20
	v_exp_f32_e32 v21, v21
	v_exp_f32_e32 v22, v22
	v_exp_f32_e32 v23, v23
	v_exp_f32_e32 v24, v24
	v_exp_f32_e32 v25, v25
	v_exp_f32_e32 v26, v26
	v_exp_f32_e32 v27, v27
	v_exp_f32_e32 v28, v28
	v_exp_f32_e32 v29, v29
	v_exp_f32_e32 v30, v30
	v_exp_f32_e32 v31, v31
	v_exp_f32_e32 v0, v0
	v_exp_f32_e32 v1, v1
	v_exp_f32_e32 v2, v2
	v_exp_f32_e32 v3, v3
	v_exp_f32_e32 v4, v4
	v_exp_f32_e32 v5, v5
	v_exp_f32_e32 v6, v6
	v_exp_f32_e32 v7, v7
	v_exp_f32_e32 v8, v8
	v_exp_f32_e32 v9, v9
	v_exp_f32_e32 v10, v10
	v_exp_f32_e32 v11, v11
	v_exp_f32_e32 v12, v12
	v_exp_f32_e32 v13, v13
	v_exp_f32_e32 v14, v14
	v_exp_f32_e32 v15, v15
	v_add_f32_e32 v144, v16, v17
	v_add_f32_e32 v145, v18, v19
	v_add_f32_e32 v146, v20, v21
	v_add_f32_e32 v147, v22, v23
	v_add_f32_e32 v148, v24, v25
	v_add_f32_e32 v149, v26, v27
	v_add_f32_e32 v150, v28, v29
	v_add_f32_e32 v151, v30, v31
	v_add_f32_e32 v152, v0, v1
	v_add_f32_e32 v153, v2, v3
	v_add_f32_e32 v154, v4, v5
	v_add_f32_e32 v155, v6, v7
	v_add_f32_e32 v156, v8, v9
	v_add_f32_e32 v157, v10, v11
	v_add_f32_e32 v158, v12, v13
	v_add_f32_e32 v159, v14, v15
	v_add_f32_e32 v144, v144, v152
	v_add_f32_e32 v145, v145, v153
	v_add_f32_e32 v146, v146, v154
	v_add_f32_e32 v147, v147, v155
	v_add_f32_e32 v148, v148, v156
	v_add_f32_e32 v149, v149, v157
	v_add_f32_e32 v150, v150, v158
	v_add_f32_e32 v151, v151, v159
	v_add_f32_e32 v144, v144, v148
	v_add_f32_e32 v145, v145, v149
	v_add_f32_e32 v146, v146, v150
	v_add_f32_e32 v147, v147, v151
	v_add_f32_e32 v144, v144, v146
	v_add_f32_e32 v145, v145, v147
	v_add_f32_e32 v33, v144, v145
	s_nop 0
	v_mov_b32_e32 v34, v33
	s_nop 1
	v_permlane32_swap_b32_e32 v33, v34
	v_add_f32_e32 v33, v33, v34
	v_add_f32_e32 v185, 0, v33
	v_cvt_pk_bf16_f32 v156, v16, v17
	v_cvt_pk_bf16_f32 v157, v18, v19
	v_cvt_pk_bf16_f32 v158, v20, v21
	v_cvt_pk_bf16_f32 v159, v22, v23
	v_cvt_pk_bf16_f32 v152, v24, v25
	v_cvt_pk_bf16_f32 v153, v26, v27
	v_cvt_pk_bf16_f32 v154, v28, v29
	v_cvt_pk_bf16_f32 v155, v30, v31
	v_cvt_pk_bf16_f32 v148, v0, v1
	v_cvt_pk_bf16_f32 v149, v2, v3
	v_cvt_pk_bf16_f32 v150, v4, v5
	v_cvt_pk_bf16_f32 v151, v6, v7
	v_cvt_pk_bf16_f32 v144, v8, v9
	v_cvt_pk_bf16_f32 v145, v10, v11
	v_cvt_pk_bf16_f32 v146, v12, v13
	v_cvt_pk_bf16_f32 v147, v14, v15
	s_mov_b64 s[2:3], 0

.LBB0_668:
	s_nop 1
	v_exp_f32_e32 v80, v80
	v_exp_f32_e32 v81, v81
	v_exp_f32_e32 v82, v82
	v_exp_f32_e32 v83, v83
	v_exp_f32_e32 v84, v84
	v_exp_f32_e32 v85, v85
	v_exp_f32_e32 v86, v86
	v_exp_f32_e32 v87, v87
	v_exp_f32_e32 v88, v88
	v_exp_f32_e32 v89, v89
	v_exp_f32_e32 v90, v90
	v_exp_f32_e32 v91, v91
	v_exp_f32_e32 v92, v92
	v_exp_f32_e32 v93, v93
	v_exp_f32_e32 v94, v94
	v_exp_f32_e32 v95, v95
	v_exp_f32_e32 v64, v64
	v_exp_f32_e32 v65, v65
	v_exp_f32_e32 v66, v66
	v_exp_f32_e32 v67, v67
	v_exp_f32_e32 v68, v68
	v_exp_f32_e32 v69, v69
	v_exp_f32_e32 v70, v70
	v_exp_f32_e32 v71, v71
	v_exp_f32_e32 v72, v72
	v_exp_f32_e32 v73, v73
	v_exp_f32_e32 v74, v74
	v_exp_f32_e32 v75, v75
	v_exp_f32_e32 v76, v76
	v_exp_f32_e32 v77, v77
	v_exp_f32_e32 v78, v78
	v_exp_f32_e32 v79, v79
	v_add_f32_e32 v144, v80, v81
	v_add_f32_e32 v145, v82, v83
	v_add_f32_e32 v146, v84, v85
	v_add_f32_e32 v147, v86, v87
	v_add_f32_e32 v148, v88, v89
	v_add_f32_e32 v149, v90, v91
	v_add_f32_e32 v150, v92, v93
	v_add_f32_e32 v151, v94, v95
	v_add_f32_e32 v152, v64, v65
	v_add_f32_e32 v153, v66, v67
	v_add_f32_e32 v154, v68, v69
	v_add_f32_e32 v155, v70, v71
	v_add_f32_e32 v156, v72, v73
	v_add_f32_e32 v157, v74, v75
	v_add_f32_e32 v158, v76, v77
	v_add_f32_e32 v159, v78, v79
	v_add_f32_e32 v144, v144, v152
	v_add_f32_e32 v145, v145, v153
	v_add_f32_e32 v146, v146, v154
	v_add_f32_e32 v147, v147, v155
	v_add_f32_e32 v148, v148, v156
	v_add_f32_e32 v149, v149, v157
	v_add_f32_e32 v150, v150, v158
	v_add_f32_e32 v151, v151, v159
	v_add_f32_e32 v144, v144, v148
	v_add_f32_e32 v145, v145, v149
	v_add_f32_e32 v146, v146, v150
	v_add_f32_e32 v147, v147, v151
	v_add_f32_e32 v144, v144, v146
	v_add_f32_e32 v145, v145, v147
	v_add_f32_e32 v144, v144, v145
	s_nop 0
	v_mov_b32_e32 v145, v144
	s_nop 1
	v_permlane32_swap_b32_e32 v144, v145
	v_add_f32_e32 v144, v144, v145
	v_add_f32_e32 v187, v185, v144
	v_cvt_pk_bf16_f32 v156, v80, v81
	v_cvt_pk_bf16_f32 v157, v82, v83
	v_cvt_pk_bf16_f32 v158, v84, v85
	v_cvt_pk_bf16_f32 v159, v86, v87
	v_cvt_pk_bf16_f32 v152, v88, v89
	v_cvt_pk_bf16_f32 v153, v90, v91
	v_cvt_pk_bf16_f32 v154, v92, v93
	v_cvt_pk_bf16_f32 v155, v94, v95
	v_cvt_pk_bf16_f32 v148, v64, v65
	v_cvt_pk_bf16_f32 v149, v66, v67
	v_cvt_pk_bf16_f32 v150, v68, v69
	v_cvt_pk_bf16_f32 v151, v70, v71
	v_cvt_pk_bf16_f32 v144, v72, v73
	v_cvt_pk_bf16_f32 v145, v74, v75
	v_cvt_pk_bf16_f32 v146, v76, v77
	v_cvt_pk_bf16_f32 v147, v78, v79
	s_mov_b64 s[2:3], 0

.LBB0_681:
	s_nop 2
	v_exp_f32_e32 v80, v80
	v_exp_f32_e32 v81, v81
	v_exp_f32_e32 v82, v82
	v_exp_f32_e32 v83, v83
	v_exp_f32_e32 v84, v84
	v_exp_f32_e32 v85, v85
	v_exp_f32_e32 v86, v86
	v_exp_f32_e32 v87, v87
	v_exp_f32_e32 v88, v88
	v_exp_f32_e32 v89, v89
	v_exp_f32_e32 v90, v90
	v_exp_f32_e32 v91, v91
	v_exp_f32_e32 v92, v92
	v_exp_f32_e32 v93, v93
	v_exp_f32_e32 v94, v94
	v_exp_f32_e32 v95, v95
	v_exp_f32_e32 v64, v64
	v_exp_f32_e32 v65, v65
	v_exp_f32_e32 v66, v66
	v_exp_f32_e32 v67, v67
	v_exp_f32_e32 v68, v68
	v_exp_f32_e32 v69, v69
	v_exp_f32_e32 v70, v70
	v_exp_f32_e32 v71, v71
	v_exp_f32_e32 v72, v72
	v_exp_f32_e32 v73, v73
	v_exp_f32_e32 v74, v74
	v_exp_f32_e32 v75, v75
	v_exp_f32_e32 v76, v76
	v_exp_f32_e32 v77, v77
	v_exp_f32_e32 v78, v78
	v_exp_f32_e32 v79, v79
	v_add_f32_e32 v144, v80, v81
	v_add_f32_e32 v145, v82, v83
	v_add_f32_e32 v146, v84, v85
	v_add_f32_e32 v147, v86, v87
	v_add_f32_e32 v148, v88, v89
	v_add_f32_e32 v149, v90, v91
	v_add_f32_e32 v150, v92, v93
	v_add_f32_e32 v151, v94, v95
	v_add_f32_e32 v152, v64, v65
	v_add_f32_e32 v153, v66, v67
	v_add_f32_e32 v154, v68, v69
	v_add_f32_e32 v155, v70, v71
	v_add_f32_e32 v156, v72, v73
	v_add_f32_e32 v157, v74, v75
	v_add_f32_e32 v158, v76, v77
	v_add_f32_e32 v159, v78, v79
	v_add_f32_e32 v144, v144, v152
	v_add_f32_e32 v145, v145, v153
	v_add_f32_e32 v146, v146, v154
	v_add_f32_e32 v147, v147, v155
	v_add_f32_e32 v148, v148, v156
	v_add_f32_e32 v149, v149, v157
	v_add_f32_e32 v150, v150, v158
	v_add_f32_e32 v151, v151, v159
	v_add_f32_e32 v144, v144, v148
	v_add_f32_e32 v145, v145, v149
	v_add_f32_e32 v146, v146, v150
	v_add_f32_e32 v147, v147, v151
	v_add_f32_e32 v144, v144, v146
	v_add_f32_e32 v145, v145, v147
	v_add_f32_e32 v144, v144, v145
	s_nop 0
	v_mov_b32_e32 v145, v144
	s_nop 1
	v_permlane32_swap_b32_e32 v144, v145
	v_add_f32_e32 v144, v144, v145
	v_add_f32_e32 v185, v187, v144
	v_cvt_pk_bf16_f32 v156, v80, v81
	v_cvt_pk_bf16_f32 v157, v82, v83
	v_cvt_pk_bf16_f32 v158, v84, v85
	v_cvt_pk_bf16_f32 v159, v86, v87
	v_cvt_pk_bf16_f32 v152, v88, v89
	v_cvt_pk_bf16_f32 v153, v90, v91
	v_cvt_pk_bf16_f32 v154, v92, v93
	v_cvt_pk_bf16_f32 v155, v94, v95
	v_cvt_pk_bf16_f32 v148, v64, v65
	v_cvt_pk_bf16_f32 v149, v66, v67
	v_cvt_pk_bf16_f32 v150, v68, v69
	v_cvt_pk_bf16_f32 v151, v70, v71
	v_cvt_pk_bf16_f32 v144, v72, v73
	v_cvt_pk_bf16_f32 v145, v74, v75
	v_cvt_pk_bf16_f32 v146, v76, v77
	v_cvt_pk_bf16_f32 v147, v78, v79
	s_mov_b64 s[2:3], 0

.LBB0_693:
	s_nop 0
	v_exp_f32_e32 v80, v80
	v_exp_f32_e32 v81, v81
	v_exp_f32_e32 v82, v82
	v_exp_f32_e32 v83, v83
	v_exp_f32_e32 v84, v84
	v_exp_f32_e32 v85, v85
	v_exp_f32_e32 v86, v86
	v_exp_f32_e32 v87, v87
	v_exp_f32_e32 v88, v88
	v_exp_f32_e32 v89, v89
	v_exp_f32_e32 v90, v90
	v_exp_f32_e32 v91, v91
	v_exp_f32_e32 v92, v92
	v_exp_f32_e32 v93, v93
	v_exp_f32_e32 v94, v94
	v_exp_f32_e32 v95, v95
	v_exp_f32_e32 v64, v64
	v_exp_f32_e32 v65, v65
	v_exp_f32_e32 v66, v66
	v_exp_f32_e32 v67, v67
	v_exp_f32_e32 v68, v68
	v_exp_f32_e32 v69, v69
	v_exp_f32_e32 v70, v70
	v_exp_f32_e32 v71, v71
	v_exp_f32_e32 v72, v72
	v_exp_f32_e32 v73, v73
	v_exp_f32_e32 v74, v74
	v_exp_f32_e32 v75, v75
	v_exp_f32_e32 v76, v76
	v_exp_f32_e32 v77, v77
	v_exp_f32_e32 v78, v78
	v_exp_f32_e32 v79, v79
	v_add_f32_e32 v144, v80, v81
	v_add_f32_e32 v145, v82, v83
	v_add_f32_e32 v146, v84, v85
	v_add_f32_e32 v147, v86, v87
	v_add_f32_e32 v148, v88, v89
	v_add_f32_e32 v149, v90, v91
	v_add_f32_e32 v150, v92, v93
	v_add_f32_e32 v151, v94, v95
	v_add_f32_e32 v152, v64, v65
	v_add_f32_e32 v153, v66, v67
	v_add_f32_e32 v154, v68, v69
	v_add_f32_e32 v155, v70, v71
	v_add_f32_e32 v156, v72, v73
	v_add_f32_e32 v157, v74, v75
	v_add_f32_e32 v158, v76, v77
	v_add_f32_e32 v159, v78, v79
	v_add_f32_e32 v144, v144, v152
	v_add_f32_e32 v145, v145, v153
	v_add_f32_e32 v146, v146, v154
	v_add_f32_e32 v147, v147, v155
	v_add_f32_e32 v148, v148, v156
	v_add_f32_e32 v149, v149, v157
	v_add_f32_e32 v150, v150, v158
	v_add_f32_e32 v151, v151, v159
	v_add_f32_e32 v144, v144, v148
	v_add_f32_e32 v145, v145, v149
	v_add_f32_e32 v146, v146, v150
	v_add_f32_e32 v147, v147, v151
	v_add_f32_e32 v144, v144, v146
	v_add_f32_e32 v145, v145, v147
	v_add_f32_e32 v112, v144, v145
	s_nop 0
	v_mov_b32_e32 v113, v112
	s_nop 1
	v_permlane32_swap_b32_e32 v112, v113
	v_add_f32_e32 v112, v112, v113
	v_add_f32_e32 v165, v185, v112
	v_cvt_pk_bf16_f32 v156, v80, v81
	v_cvt_pk_bf16_f32 v157, v82, v83
	v_cvt_pk_bf16_f32 v158, v84, v85
	v_cvt_pk_bf16_f32 v159, v86, v87
	v_cvt_pk_bf16_f32 v152, v88, v89
	v_cvt_pk_bf16_f32 v153, v90, v91
	v_cvt_pk_bf16_f32 v154, v92, v93
	v_cvt_pk_bf16_f32 v155, v94, v95
	v_cvt_pk_bf16_f32 v148, v64, v65
	v_cvt_pk_bf16_f32 v149, v66, v67
	v_cvt_pk_bf16_f32 v150, v68, v69
	v_cvt_pk_bf16_f32 v151, v70, v71
	v_cvt_pk_bf16_f32 v144, v72, v73
	v_cvt_pk_bf16_f32 v145, v74, v75
	v_cvt_pk_bf16_f32 v146, v76, v77
	v_cvt_pk_bf16_f32 v147, v78, v79
	s_mov_b64 s[2:3], 0
